# S5 phases: transpose waves paced with s_sleep 90 per item, plus ssq reduction in the Zt read shadow
# baseline (speedup 1.0000x reference)
.LBB0_280:
	s_sleep 90
	s_add_i32 s1, s1, s73
	s_add_i32 s4, s4, s73
	s_add_i32 s5, s1, 0xffffd000
	s_cmpk_lt_i32 s5, 0x3000
	s_cbranch_scc0 .LBB0_319
